# final RMSNorm processes 4 rows per wave-iteration with the gain vector loaded once (same per-row arithmetic order)
# speedup vs baseline: 1.0409x; 1.0029x over previous
; __device__ __forceinline__ void phase_final(const Params& p) {
;     ...
;   const int gw = blockIdx.x * NW + (tid >> 6), tw = gridDim.x * NW;
;   const float* nw = p.in[32];
;   for (int r = gw; r < ML; r += tw) {
;     float* xr = p.out + (size_t)r * 1024;
;     float4 v[4];
;     float ss = 0.f;
; #pragma unroll
;     for (int i = 0; i < 4; ++i) {
;       v[i] = *reinterpret_cast<const float4*>(xr + i * 256 + lane * 4);
;       ss += v[i].x * v[i].x + v[i].y * v[i].y + v[i].z * v[i].z + v[i].w * v[i].w;
.LBB0_1730:
	s_mov_b32 s0, 0x10000
	v_ashrrev_i32_e32 v0, 6, v176
	v_lshl_add_u32 v0, s68, 3, v0
	v_cmp_gt_i32_e32 vcc, s0, v0
	s_and_saveexec_b64 s[0:1], vcc
	s_cbranch_execz .LBB0_1733
	v_lshlrev_b32_e32 v1, 4, v176
	v_and_b32_e32 v2, 0x3f0, v1
	v_xor_b32_e32 v1, 32, v179
	v_cmp_lt_i32_e32 vcc, v1, v178
	s_lshl_b32 s0, s78, 3
	v_mov_b32_e32 v3, 0
	v_cndmask_b32_e32 v1, v179, v1, vcc
	v_lshlrev_b32_e32 v6, 2, v1
	v_xor_b32_e32 v1, 16, v179
	v_cmp_lt_i32_e32 vcc, v1, v178
	s_ashr_i32 s1, s0, 31
	v_lshl_add_u64 v[2:3], s[72:73], 0, v[2:3]
	v_cndmask_b32_e32 v1, v179, v1, vcc
	v_lshlrev_b32_e32 v7, 2, v1
	v_xor_b32_e32 v1, 8, v179
	v_cmp_lt_i32_e32 vcc, v1, v178
	s_lshl_b64 s[2:3], s[0:1], 12
	s_mov_b64 s[4:5], 0
	v_cndmask_b32_e32 v1, v179, v1, vcc
	v_lshlrev_b32_e32 v8, 2, v1
	v_xor_b32_e32 v1, 4, v179
	v_cmp_lt_i32_e32 vcc, v1, v178
	s_mov_b32 s1, 0x800000
	s_mov_b32 s6, 0xffff
	v_cndmask_b32_e32 v1, v179, v1, vcc
	v_lshlrev_b32_e32 v9, 2, v1
	v_xor_b32_e32 v1, 2, v179
	v_cmp_lt_i32_e32 vcc, v1, v178
	s_nop 1
	v_cndmask_b32_e32 v1, v179, v1, vcc
	v_lshlrev_b32_e32 v10, 2, v1
	v_xor_b32_e32 v1, 1, v179
	v_cmp_lt_i32_e32 vcc, v1, v178
	s_nop 1
	v_cndmask_b32_e32 v1, v179, v1, vcc
	v_lshlrev_b32_e32 v11, 2, v1
	v_ashrrev_i32_e32 v1, 31, v0
	v_lshlrev_b64 v[4:5], 12, v[0:1]
	v_and_b32_e32 v1, 63, v176
	v_lshl_or_b32 v4, v1, 4, v4
	v_lshl_add_u64 v[4:5], s[74:75], 0, v[4:5]
	v_mov_b32_e32 v1, 0x358637bd
	global_load_dwordx4 v[48:51], v[2:3], off
	global_load_dwordx4 v[52:55], v[2:3], off offset:1024
	global_load_dwordx4 v[56:59], v[2:3], off offset:2048
	global_load_dwordx4 v[60:63], v[2:3], off offset:3072
	s_mul_i32 s8, s0, 3
.Lfin4_loop:
	v_readfirstlane_b32 s9, v0
	s_add_i32 s9, s9, s8
	s_cmp_gt_i32 s9, s6
	s_cbranch_scc1 .Lfin4_done
	v_lshl_add_u64 v[152:153], v[4:5], 0, s[2:3]
	v_lshl_add_u64 v[154:155], v[152:153], 0, s[2:3]
	v_lshl_add_u64 v[156:157], v[154:155], 0, s[2:3]
	global_load_dwordx4 v[64:67], v[4:5], off
	global_load_dwordx4 v[68:71], v[4:5], off offset:1024
	global_load_dwordx4 v[72:75], v[4:5], off offset:2048
	global_load_dwordx4 v[76:79], v[4:5], off offset:3072
	global_load_dwordx4 v[80:83], v[152:153], off
	global_load_dwordx4 v[84:87], v[152:153], off offset:1024
	global_load_dwordx4 v[88:91], v[152:153], off offset:2048
	global_load_dwordx4 v[92:95], v[152:153], off offset:3072
	global_load_dwordx4 v[96:99], v[154:155], off
	global_load_dwordx4 v[100:103], v[154:155], off offset:1024
	global_load_dwordx4 v[104:107], v[154:155], off offset:2048
	global_load_dwordx4 v[108:111], v[154:155], off offset:3072
	global_load_dwordx4 v[112:115], v[156:157], off
	global_load_dwordx4 v[116:119], v[156:157], off offset:1024
	global_load_dwordx4 v[120:123], v[156:157], off offset:2048
	global_load_dwordx4 v[124:127], v[156:157], off offset:3072
	s_waitcnt vmcnt(12)
	v_mov_b32_e32 v140, v65
	v_mov_b32_e32 v141, v69
	v_mov_b32_e32 v132, v64
	v_mov_b32_e32 v133, v68
	v_pk_mul_f32 v[140:141], v[140:141], v[140:141]
	v_pk_fma_f32 v[132:133], v[132:133], v[132:133], v[140:141]
	v_mov_b32_e32 v158, v73
	v_mov_b32_e32 v159, v77
	v_mov_b32_e32 v160, v72
	v_mov_b32_e32 v161, v76
	v_pk_mul_f32 v[158:159], v[158:159], v[158:159]
	v_pk_fma_f32 v[140:141], v[160:161], v[160:161], v[158:159]
	v_mov_b32_e32 v158, v66
	v_mov_b32_e32 v159, v70
	v_pk_fma_f32 v[132:133], v[158:159], v[158:159], v[132:133]
	v_mov_b32_e32 v160, v74
	v_mov_b32_e32 v161, v78
	v_pk_fma_f32 v[140:141], v[160:161], v[160:161], v[140:141]
	v_mov_b32_e32 v158, v67
	v_mov_b32_e32 v159, v71
	v_pk_fma_f32 v[132:133], v[158:159], v[158:159], v[132:133]
	v_mov_b32_e32 v160, v75
	v_mov_b32_e32 v161, v79
	v_pk_fma_f32 v[140:141], v[160:161], v[160:161], v[140:141]
	v_add_f32_e32 v132, v132, v133
	v_add_f32_e32 v132, v132, v140
	v_add_f32_e32 v132, v132, v141
	s_waitcnt vmcnt(8)
	v_mov_b32_e32 v142, v81
	v_mov_b32_e32 v143, v85
	v_mov_b32_e32 v134, v80
	v_mov_b32_e32 v135, v84
	v_pk_mul_f32 v[142:143], v[142:143], v[142:143]
	v_pk_fma_f32 v[134:135], v[134:135], v[134:135], v[142:143]
	v_mov_b32_e32 v158, v89
	v_mov_b32_e32 v159, v93
	v_mov_b32_e32 v160, v88
	v_mov_b32_e32 v161, v92
	v_pk_mul_f32 v[158:159], v[158:159], v[158:159]
	v_pk_fma_f32 v[142:143], v[160:161], v[160:161], v[158:159]
	v_mov_b32_e32 v158, v82
	v_mov_b32_e32 v159, v86
	v_pk_fma_f32 v[134:135], v[158:159], v[158:159], v[134:135]
	v_mov_b32_e32 v160, v90
	v_mov_b32_e32 v161, v94
	v_pk_fma_f32 v[142:143], v[160:161], v[160:161], v[142:143]
	v_mov_b32_e32 v158, v83
	v_mov_b32_e32 v159, v87
	v_pk_fma_f32 v[134:135], v[158:159], v[158:159], v[134:135]
	v_mov_b32_e32 v160, v91
	v_mov_b32_e32 v161, v95
	v_pk_fma_f32 v[142:143], v[160:161], v[160:161], v[142:143]
	v_add_f32_e32 v134, v134, v135
	v_add_f32_e32 v134, v134, v142
	v_add_f32_e32 v134, v134, v143
	s_waitcnt vmcnt(4)
	v_mov_b32_e32 v144, v97
	v_mov_b32_e32 v145, v101
	v_mov_b32_e32 v136, v96
	v_mov_b32_e32 v137, v100
	v_pk_mul_f32 v[144:145], v[144:145], v[144:145]
	v_pk_fma_f32 v[136:137], v[136:137], v[136:137], v[144:145]
	v_mov_b32_e32 v158, v105
	v_mov_b32_e32 v159, v109
	v_mov_b32_e32 v160, v104
	v_mov_b32_e32 v161, v108
	v_pk_mul_f32 v[158:159], v[158:159], v[158:159]
	v_pk_fma_f32 v[144:145], v[160:161], v[160:161], v[158:159]
	v_mov_b32_e32 v158, v98
	v_mov_b32_e32 v159, v102
	v_pk_fma_f32 v[136:137], v[158:159], v[158:159], v[136:137]
	v_mov_b32_e32 v160, v106
	v_mov_b32_e32 v161, v110
	v_pk_fma_f32 v[144:145], v[160:161], v[160:161], v[144:145]
	v_mov_b32_e32 v158, v99
	v_mov_b32_e32 v159, v103
	v_pk_fma_f32 v[136:137], v[158:159], v[158:159], v[136:137]
	v_mov_b32_e32 v160, v107
	v_mov_b32_e32 v161, v111
	v_pk_fma_f32 v[144:145], v[160:161], v[160:161], v[144:145]
	v_add_f32_e32 v136, v136, v137
	v_add_f32_e32 v136, v136, v144
	v_add_f32_e32 v136, v136, v145
	s_waitcnt vmcnt(0)
; __device__ __forceinline__ void phase_final(const Params& p) {
;     ...
;       ss += v[i].x * v[i].x + v[i].y * v[i].y + v[i].z * v[i].z + v[i].w * v[i].w;
;     }
; #pragma unroll
;     for (int o = 32; o >= 1; o >>= 1) ss += __shfl_xor(ss, o);
	v_mov_b32_e32 v146, v113
	v_mov_b32_e32 v147, v117
	v_mov_b32_e32 v138, v112
	v_mov_b32_e32 v139, v116
	v_pk_mul_f32 v[146:147], v[146:147], v[146:147]
	v_pk_fma_f32 v[138:139], v[138:139], v[138:139], v[146:147]
	v_mov_b32_e32 v158, v121
	v_mov_b32_e32 v159, v125
	v_mov_b32_e32 v160, v120
	v_mov_b32_e32 v161, v124
	v_pk_mul_f32 v[158:159], v[158:159], v[158:159]
	v_pk_fma_f32 v[146:147], v[160:161], v[160:161], v[158:159]
	v_mov_b32_e32 v158, v114
	v_mov_b32_e32 v159, v118
	v_pk_fma_f32 v[138:139], v[158:159], v[158:159], v[138:139]
	v_mov_b32_e32 v160, v122
	v_mov_b32_e32 v161, v126
	v_pk_fma_f32 v[146:147], v[160:161], v[160:161], v[146:147]
	v_mov_b32_e32 v158, v115
	v_mov_b32_e32 v159, v119
	v_pk_fma_f32 v[138:139], v[158:159], v[158:159], v[138:139]
	v_mov_b32_e32 v160, v123
	v_mov_b32_e32 v161, v127
	v_pk_fma_f32 v[146:147], v[160:161], v[160:161], v[146:147]
	v_add_f32_e32 v138, v138, v139
	v_add_f32_e32 v138, v138, v146
	v_add_f32_e32 v138, v138, v147
	ds_bpermute_b32 v148, v6, v132
	ds_bpermute_b32 v149, v6, v134
	ds_bpermute_b32 v150, v6, v136
	ds_bpermute_b32 v151, v6, v138
	s_waitcnt lgkmcnt(3)
	v_add_f32_e32 v132, v132, v148
	s_waitcnt lgkmcnt(2)
	v_add_f32_e32 v134, v134, v149
	s_waitcnt lgkmcnt(1)
	v_add_f32_e32 v136, v136, v150
	s_waitcnt lgkmcnt(0)
	v_add_f32_e32 v138, v138, v151
	ds_bpermute_b32 v148, v7, v132
	ds_bpermute_b32 v149, v7, v134
	ds_bpermute_b32 v150, v7, v136
	ds_bpermute_b32 v151, v7, v138
	s_waitcnt lgkmcnt(3)
	v_add_f32_e32 v132, v132, v148
	s_waitcnt lgkmcnt(2)
	v_add_f32_e32 v134, v134, v149
	s_waitcnt lgkmcnt(1)
	v_add_f32_e32 v136, v136, v150
	s_waitcnt lgkmcnt(0)
	v_add_f32_e32 v138, v138, v151
	ds_bpermute_b32 v148, v8, v132
	ds_bpermute_b32 v149, v8, v134
	ds_bpermute_b32 v150, v8, v136
	ds_bpermute_b32 v151, v8, v138
	s_waitcnt lgkmcnt(3)
	v_add_f32_e32 v132, v132, v148
	s_waitcnt lgkmcnt(2)
	v_add_f32_e32 v134, v134, v149
	s_waitcnt lgkmcnt(1)
	v_add_f32_e32 v136, v136, v150
	s_waitcnt lgkmcnt(0)
	v_add_f32_e32 v138, v138, v151
	ds_bpermute_b32 v148, v9, v132
	ds_bpermute_b32 v149, v9, v134
	ds_bpermute_b32 v150, v9, v136
	ds_bpermute_b32 v151, v9, v138
	s_waitcnt lgkmcnt(3)
	v_add_f32_e32 v132, v132, v148
	s_waitcnt lgkmcnt(2)
	v_add_f32_e32 v134, v134, v149
	s_waitcnt lgkmcnt(1)
	v_add_f32_e32 v136, v136, v150
	s_waitcnt lgkmcnt(0)
	v_add_f32_e32 v138, v138, v151
	ds_bpermute_b32 v148, v10, v132
	ds_bpermute_b32 v149, v10, v134
	ds_bpermute_b32 v150, v10, v136
	ds_bpermute_b32 v151, v10, v138
	s_waitcnt lgkmcnt(3)
	v_add_f32_e32 v132, v132, v148
	s_waitcnt lgkmcnt(2)
	v_add_f32_e32 v134, v134, v149
	s_waitcnt lgkmcnt(1)
	v_add_f32_e32 v136, v136, v150
	s_waitcnt lgkmcnt(0)
	v_add_f32_e32 v138, v138, v151
	ds_bpermute_b32 v148, v11, v132
	ds_bpermute_b32 v149, v11, v134
	ds_bpermute_b32 v150, v11, v136
	ds_bpermute_b32 v151, v11, v138
	s_waitcnt lgkmcnt(3)
	v_add_f32_e32 v132, v132, v148
	s_waitcnt lgkmcnt(2)
	v_add_f32_e32 v134, v134, v149
	s_waitcnt lgkmcnt(1)
	v_add_f32_e32 v136, v136, v150
	s_waitcnt lgkmcnt(0)
; __device__ __forceinline__ void phase_final(const Params& p) {
;     ...
;     const float rs = rsqrtf(ss * (1.f / 1024.f) + EPS);
; #pragma unroll
;     for (int i = 0; i < 4; ++i) {
;       const float4 g = *reinterpret_cast<const float4*>(nw + i * 256 + lane * 4);
;       float4 o;
;       o.x = v[i].x * rs * g.x; o.y = v[i].y * rs * g.y; o.z = v[i].z * rs * g.z; o.w = v[i].w * rs * g.w;
;       *reinterpret_cast<float4*>(xr + i * 256 + lane * 4) = o;
;     }
;   }
	v_add_f32_e32 v138, v138, v151
	v_fmamk_f32 v132, v132, 0x3a800000, v1
	v_mul_f32_e32 v133, 0x4b800000, v132
	v_cmp_gt_f32_e32 vcc, s1, v132
	s_nop 1
	v_cndmask_b32_e32 v132, v132, v133, vcc
	v_rsq_f32_e32 v132, v132
	s_nop 0
	v_mul_f32_e32 v133, 0x45800000, v132
	v_cndmask_b32_e32 v132, v132, v133, vcc
	v_pk_mul_f32 v[64:65], v[64:65], v[132:133] op_sel_hi:[1,0]
	v_pk_mul_f32 v[66:67], v[66:67], v[132:133] op_sel_hi:[1,0]
	v_pk_mul_f32 v[68:69], v[68:69], v[132:133] op_sel_hi:[1,0]
	v_pk_mul_f32 v[70:71], v[70:71], v[132:133] op_sel_hi:[1,0]
	v_pk_mul_f32 v[72:73], v[72:73], v[132:133] op_sel_hi:[1,0]
	v_pk_mul_f32 v[74:75], v[74:75], v[132:133] op_sel_hi:[1,0]
	v_pk_mul_f32 v[76:77], v[76:77], v[132:133] op_sel_hi:[1,0]
	v_pk_mul_f32 v[78:79], v[78:79], v[132:133] op_sel_hi:[1,0]
	v_pk_mul_f32 v[64:65], v[48:49], v[64:65]
	v_pk_mul_f32 v[66:67], v[50:51], v[66:67]
	v_pk_mul_f32 v[68:69], v[52:53], v[68:69]
	v_pk_mul_f32 v[70:71], v[54:55], v[70:71]
	v_pk_mul_f32 v[72:73], v[56:57], v[72:73]
	v_pk_mul_f32 v[74:75], v[58:59], v[74:75]
	v_pk_mul_f32 v[76:77], v[60:61], v[76:77]
	v_pk_mul_f32 v[78:79], v[62:63], v[78:79]
	global_store_dwordx4 v[4:5], v[64:67], off
	global_store_dwordx4 v[4:5], v[68:71], off offset:1024
	global_store_dwordx4 v[4:5], v[72:75], off offset:2048
	global_store_dwordx4 v[4:5], v[76:79], off offset:3072
	v_fmamk_f32 v134, v134, 0x3a800000, v1
	v_mul_f32_e32 v135, 0x4b800000, v134
	v_cmp_gt_f32_e32 vcc, s1, v134
	s_nop 1
	v_cndmask_b32_e32 v134, v134, v135, vcc
	v_rsq_f32_e32 v134, v134
	s_nop 0
	v_mul_f32_e32 v135, 0x45800000, v134
	v_cndmask_b32_e32 v134, v134, v135, vcc
	v_pk_mul_f32 v[80:81], v[80:81], v[134:135] op_sel_hi:[1,0]
	v_pk_mul_f32 v[82:83], v[82:83], v[134:135] op_sel_hi:[1,0]
	v_pk_mul_f32 v[84:85], v[84:85], v[134:135] op_sel_hi:[1,0]
	v_pk_mul_f32 v[86:87], v[86:87], v[134:135] op_sel_hi:[1,0]
	v_pk_mul_f32 v[88:89], v[88:89], v[134:135] op_sel_hi:[1,0]
	v_pk_mul_f32 v[90:91], v[90:91], v[134:135] op_sel_hi:[1,0]
	v_pk_mul_f32 v[92:93], v[92:93], v[134:135] op_sel_hi:[1,0]
	v_pk_mul_f32 v[94:95], v[94:95], v[134:135] op_sel_hi:[1,0]
	v_pk_mul_f32 v[80:81], v[48:49], v[80:81]
	v_pk_mul_f32 v[82:83], v[50:51], v[82:83]
	v_pk_mul_f32 v[84:85], v[52:53], v[84:85]
	v_pk_mul_f32 v[86:87], v[54:55], v[86:87]
	v_pk_mul_f32 v[88:89], v[56:57], v[88:89]
	v_pk_mul_f32 v[90:91], v[58:59], v[90:91]
	v_pk_mul_f32 v[92:93], v[60:61], v[92:93]
	v_pk_mul_f32 v[94:95], v[62:63], v[94:95]
	global_store_dwordx4 v[152:153], v[80:83], off
	global_store_dwordx4 v[152:153], v[84:87], off offset:1024
	global_store_dwordx4 v[152:153], v[88:91], off offset:2048
	global_store_dwordx4 v[152:153], v[92:95], off offset:3072
	v_fmamk_f32 v136, v136, 0x3a800000, v1
	v_mul_f32_e32 v137, 0x4b800000, v136
	v_cmp_gt_f32_e32 vcc, s1, v136
	s_nop 1
	v_cndmask_b32_e32 v136, v136, v137, vcc
	v_rsq_f32_e32 v136, v136
	s_nop 0
	v_mul_f32_e32 v137, 0x45800000, v136
	v_cndmask_b32_e32 v136, v136, v137, vcc
	v_pk_mul_f32 v[96:97], v[96:97], v[136:137] op_sel_hi:[1,0]
	v_pk_mul_f32 v[98:99], v[98:99], v[136:137] op_sel_hi:[1,0]
	v_pk_mul_f32 v[100:101], v[100:101], v[136:137] op_sel_hi:[1,0]
	v_pk_mul_f32 v[102:103], v[102:103], v[136:137] op_sel_hi:[1,0]
	v_pk_mul_f32 v[104:105], v[104:105], v[136:137] op_sel_hi:[1,0]
	v_pk_mul_f32 v[106:107], v[106:107], v[136:137] op_sel_hi:[1,0]
	v_pk_mul_f32 v[108:109], v[108:109], v[136:137] op_sel_hi:[1,0]
	v_pk_mul_f32 v[110:111], v[110:111], v[136:137] op_sel_hi:[1,0]
	v_pk_mul_f32 v[96:97], v[48:49], v[96:97]
	v_pk_mul_f32 v[98:99], v[50:51], v[98:99]
	v_pk_mul_f32 v[100:101], v[52:53], v[100:101]
	v_pk_mul_f32 v[102:103], v[54:55], v[102:103]
	v_pk_mul_f32 v[104:105], v[56:57], v[104:105]
	v_pk_mul_f32 v[106:107], v[58:59], v[106:107]
	v_pk_mul_f32 v[108:109], v[60:61], v[108:109]
	v_pk_mul_f32 v[110:111], v[62:63], v[110:111]
	global_store_dwordx4 v[154:155], v[96:99], off
	global_store_dwordx4 v[154:155], v[100:103], off offset:1024
	global_store_dwordx4 v[154:155], v[104:107], off offset:2048
	global_store_dwordx4 v[154:155], v[108:111], off offset:3072
	v_fmamk_f32 v138, v138, 0x3a800000, v1
	v_mul_f32_e32 v139, 0x4b800000, v138
	v_cmp_gt_f32_e32 vcc, s1, v138
	s_nop 1
	v_cndmask_b32_e32 v138, v138, v139, vcc
	v_rsq_f32_e32 v138, v138
	s_nop 0
	v_mul_f32_e32 v139, 0x45800000, v138
	v_cndmask_b32_e32 v138, v138, v139, vcc
	v_pk_mul_f32 v[112:113], v[112:113], v[138:139] op_sel_hi:[1,0]
	v_pk_mul_f32 v[114:115], v[114:115], v[138:139] op_sel_hi:[1,0]
	v_pk_mul_f32 v[116:117], v[116:117], v[138:139] op_sel_hi:[1,0]
	v_pk_mul_f32 v[118:119], v[118:119], v[138:139] op_sel_hi:[1,0]
	v_pk_mul_f32 v[120:121], v[120:121], v[138:139] op_sel_hi:[1,0]
	v_pk_mul_f32 v[122:123], v[122:123], v[138:139] op_sel_hi:[1,0]
	v_pk_mul_f32 v[124:125], v[124:125], v[138:139] op_sel_hi:[1,0]
	v_pk_mul_f32 v[126:127], v[126:127], v[138:139] op_sel_hi:[1,0]
	v_pk_mul_f32 v[112:113], v[48:49], v[112:113]
	v_pk_mul_f32 v[114:115], v[50:51], v[114:115]
	v_pk_mul_f32 v[116:117], v[52:53], v[116:117]
	v_pk_mul_f32 v[118:119], v[54:55], v[118:119]
	v_pk_mul_f32 v[120:121], v[56:57], v[120:121]
	v_pk_mul_f32 v[122:123], v[58:59], v[122:123]
	v_pk_mul_f32 v[124:125], v[60:61], v[124:125]
	v_pk_mul_f32 v[126:127], v[62:63], v[126:127]
	global_store_dwordx4 v[156:157], v[112:115], off
	global_store_dwordx4 v[156:157], v[116:119], off offset:1024
	global_store_dwordx4 v[156:157], v[120:123], off offset:2048
	global_store_dwordx4 v[156:157], v[124:127], off offset:3072
	v_lshl_add_u32 v0, s0, 2, v0
	v_lshl_add_u64 v[4:5], v[156:157], 0, s[2:3]
	s_branch .Lfin4_loop
.Lfin4_done:
	v_cmp_gt_i32_e32 vcc, 0x10000, v0
	s_and_b64 exec, exec, vcc
	s_cbranch_execz .LBB0_1733
